# gdn_passA conv stage: k/v-part window loads issued with the q-part loads (one round trip instead of three)
# baseline (speedup 1.0000x reference)
.LBB0_408:
	s_and_b32 s4, s6, 31
	s_ashr_i32 s22, s6, 7
	v_ashrrev_i32_e32 v99, 3, v100
	v_lshl_add_u32 v32, s4, 6, v99
	s_ashr_i32 s23, s22, 31
	s_lshl_b64 s[24:25], s[22:23], 11
	v_ashrrev_i32_e32 v33, 31, v32
	v_lshl_add_u64 v[102:103], s[24:25], 0, v[32:33]
	v_lshl_add_u64 v[0:1], v[102:103], 0, -3
	v_cmp_lt_i32_e32 vcc, 2, v32
	v_and_b32_e32 v101, 7, v100
	v_mov_b64_e32 v[8:9], s[14:15]
	v_subrev_u32_e32 v96, 61, v99
	v_cndmask_b32_e32 v0, v102, v0, vcc
	v_lshlrev_b32_e32 v134, 4, v101
	v_mad_i64_i32 v[58:59], s[22:23], s22, 3, v[96:97]
	v_cndmask_b32_e32 v2, v103, v1, vcc
	v_mad_u64_u32 v[0:1], s[22:23], v0, s51, v[8:9]
	v_lshl_or_b32 v133, s7, 7, v134
	v_mad_i32_i24 v1, v2, s51, v1
	v_lshl_add_u64 v[94:95], v[0:1], 0, s[18:19]
	v_lshlrev_b32_e32 v96, 1, v133
	v_lshl_add_u64 v[0:1], v[94:95], 0, v[96:97]
	global_load_dwordx4 v[28:31], v[0:1], off
	s_nop 0
	global_load_dwordx4 v[0:3], v[0:1], off offset:16
	v_cndmask_b32_e64 v104, 0, 1.0, vcc
	v_cmp_lt_i32_e32 vcc, 1, v32
	v_lshl_add_u64 v[4:5], v[102:103], 0, -2
	s_cmp_eq_u32 s4, 31
	v_cndmask_b32_e32 v4, v102, v4, vcc
	s_waitcnt vmcnt(4)
	v_cndmask_b32_e32 v6, v103, v5, vcc
	v_mad_u64_u32 v[4:5], s[22:23], v4, s51, v[8:9]
	v_mad_i32_i24 v5, v6, s51, v5
	v_lshl_add_u64 v[112:113], v[4:5], 0, s[18:19]
	v_lshl_add_u64 v[4:5], v[112:113], 0, v[96:97]
	global_load_dwordx4 v[24:27], v[4:5], off
	s_nop 0
	global_load_dwordx4 v[4:7], v[4:5], off offset:16
	v_cndmask_b32_e64 v106, 0, 1.0, vcc
	v_cmp_lt_i32_e32 vcc, 0, v32
	s_cselect_b64 s[4:5], -1, 0
	v_lshlrev_b32_e32 v120, 2, v133
	v_cndmask_b32_e64 v10, 0, 1, vcc
	v_cndmask_b32_e64 v108, 0, 1.0, vcc
	v_sub_co_u32_e32 v10, vcc, v102, v10
	v_mad_u64_u32 v[10:11], s[22:23], v10, s51, v[8:9]
	s_nop 0
	v_subbrev_co_u32_e32 v12, vcc, 0, v103, vcc
	v_mad_i32_i24 v11, v12, s51, v11
	v_lshl_add_u64 v[114:115], v[10:11], 0, s[18:19]
	v_lshl_add_u64 v[10:11], v[114:115], 0, v[96:97]
	global_load_dwordx4 v[16:19], v[10:11], off
	v_lshl_add_u32 v12, v101, 6, 0
	v_add_u32_e32 v132, 0x1d700, v12
	ds_read_b128 v[44:47], v132
	ds_read_b128 v[40:43], v132 offset:16
	ds_read_b128 v[36:39], v132 offset:48
	v_mad_u64_u32 v[12:13], s[22:23], v102, s51, v[8:9]
	global_load_dwordx4 v[8:11], v[10:11], off offset:16
	v_mad_i32_i24 v13, v103, s51, v13
	v_lshl_add_u64 v[116:117], v[12:13], 0, s[18:19]
	v_lshl_add_u64 v[122:123], v[116:117], 0, v[96:97]
	s_waitcnt lgkmcnt(2)
	v_pk_mul_f32 v[12:13], v[104:105], v[44:45] op_sel_hi:[0,1]
	s_waitcnt lgkmcnt(0)
	v_pk_mul_f32 v[14:15], v[104:105], v[38:39] op_sel_hi:[0,1]
	v_cmp_lt_i32_e32 vcc, -1, v32
	s_waitcnt vmcnt(5)
	v_lshlrev_b32_e32 v20, 16, v28
	v_and_b32_e32 v21, 0xffff0000, v28
	s_waitcnt vmcnt(4)
	v_lshlrev_b32_e32 v22, 16, v3
	v_and_b32_e32 v3, 0xffff0000, v3
	v_fma_f32 v38, v12, v20, 0
	v_fma_f32 v28, v13, v21, 0
	v_fma_f32 v45, v14, v22, 0
	v_fma_f32 v44, v15, v3, 0
	global_load_dwordx4 v[20:23], v[122:123], off
	global_load_dwordx4 v[12:15], v[122:123], off offset:16
	v_lshl_add_u64 v[224:225], v[94:95], 0, v[96:97]
	global_load_dwordx4 v[160:163], v[224:225], off offset:1024
	global_load_dwordx4 v[164:167], v[224:225], off offset:1040
	global_load_dwordx4 v[192:195], v[224:225], off offset:2048
	global_load_dwordx4 v[196:199], v[224:225], off offset:2064
	v_lshl_add_u64 v[224:225], v[112:113], 0, v[96:97]
	global_load_dwordx4 v[168:171], v[224:225], off offset:1024
	global_load_dwordx4 v[172:175], v[224:225], off offset:1040
	global_load_dwordx4 v[200:203], v[224:225], off offset:2048
	global_load_dwordx4 v[204:207], v[224:225], off offset:2064
	v_lshl_add_u64 v[224:225], v[114:115], 0, v[96:97]
	global_load_dwordx4 v[176:179], v[224:225], off offset:1024
	global_load_dwordx4 v[180:183], v[224:225], off offset:1040
	global_load_dwordx4 v[208:211], v[224:225], off offset:2048
	global_load_dwordx4 v[212:215], v[224:225], off offset:2064
	v_lshl_add_u64 v[224:225], v[116:117], 0, v[96:97]
	global_load_dwordx4 v[184:187], v[224:225], off offset:1024
	global_load_dwordx4 v[188:191], v[224:225], off offset:1040
	global_load_dwordx4 v[216:219], v[224:225], off offset:2048
	global_load_dwordx4 v[220:223], v[224:225], off offset:2064
	ds_read_b128 v[70:73], v132 offset:32
	ds_read_b128 v[48:51], v132 offset:512
	ds_read_b128 v[66:69], v132 offset:528
	ds_read_b128 v[52:55], v132 offset:560
	ds_read_b128 v[74:77], v132 offset:544
	s_waitcnt vmcnt(5)
	v_lshlrev_b32_e32 v3, 16, v24
	s_waitcnt lgkmcnt(3)
	v_pk_mul_f32 v[34:35], v[106:107], v[48:49] op_sel_hi:[0,1]
	v_fmac_f32_e32 v38, v34, v3
	v_and_b32_e32 v3, 0xffff0000, v24
	v_fmac_f32_e32 v28, v35, v3
	s_waitcnt vmcnt(4)
	v_lshlrev_b32_e32 v3, 16, v7
	s_waitcnt lgkmcnt(1)
	v_pk_mul_f32 v[34:35], v[106:107], v[54:55] op_sel_hi:[0,1]
	v_fmac_f32_e32 v45, v34, v3
	v_and_b32_e32 v3, 0xffff0000, v7
	v_fmac_f32_e32 v44, v35, v3
	ds_read_b128 v[78:81], v132 offset:1024
	ds_read_b128 v[54:57], v132 offset:1040
	ds_read_b128 v[62:65], v132 offset:1072
	ds_read_b128 v[86:89], v132 offset:1056
	v_cndmask_b32_e64 v110, 0, 1.0, vcc
	s_waitcnt vmcnt(3)
	v_lshlrev_b32_e32 v3, 16, v16
	s_waitcnt lgkmcnt(3)
	v_pk_mul_f32 v[34:35], v[108:109], v[78:79] op_sel_hi:[0,1]
	v_fmac_f32_e32 v38, v34, v3
	v_and_b32_e32 v3, 0xffff0000, v16
	v_fmac_f32_e32 v28, v35, v3
	s_waitcnt lgkmcnt(1)
	v_pk_mul_f32 v[34:35], v[108:109], v[64:65] op_sel_hi:[0,1]
	s_waitcnt vmcnt(2)
	v_lshlrev_b32_e32 v3, 16, v11
	v_fmac_f32_e32 v45, v34, v3
	v_and_b32_e32 v3, 0xffff0000, v11
	v_fmac_f32_e32 v44, v35, v3
	ds_read_b128 v[90:93], v132 offset:1536
	ds_read_b128 v[82:85], v132 offset:1552
	v_cmp_lt_i32_e32 vcc, 60, v99
	s_and_b64 s[4:5], s[4:5], vcc
	s_waitcnt lgkmcnt(1)
	v_pk_mul_f32 v[32:33], v[110:111], v[90:91] op_sel_hi:[0,1]
	s_waitcnt vmcnt(1)
	v_lshlrev_b32_e32 v3, 16, v20
	v_fmac_f32_e32 v38, v32, v3
	v_and_b32_e32 v3, 0xffff0000, v20
	v_fmac_f32_e32 v28, v33, v3
	ds_read_b128 v[32:35], v132 offset:1584
	s_waitcnt vmcnt(0)
	v_lshlrev_b32_e32 v3, 16, v15
	s_waitcnt lgkmcnt(0)
	v_pk_mul_f32 v[34:35], v[110:111], v[34:35] op_sel_hi:[0,1]
	v_fmac_f32_e32 v45, v34, v3
	v_and_b32_e32 v3, 0xffff0000, v15
	v_fmac_f32_e32 v44, v35, v3
	v_mov_b64_e32 v[34:35], s[16:17]
	v_mad_u64_u32 v[118:119], s[22:23], v58, s52, v[34:35]
	v_mad_i32_i24 v119, v59, s52, v119
	ds_read_b128 v[58:61], v132 offset:1568
	s_and_saveexec_b64 s[22:23], s[4:5]
	s_cbranch_execz .LBB0_410
	global_load_dwordx4 v[136:139], v[122:123], off
	global_load_dwordx4 v[140:143], v[122:123], off offset:16
	v_mov_b32_e32 v121, v97
	v_lshl_add_u64 v[34:35], v[118:119], 0, v[120:121]
	s_waitcnt vmcnt(1)
	v_lshlrev_b32_e32 v144, 16, v136
	v_and_b32_e32 v145, 0xffff0000, v136
	v_lshlrev_b32_e32 v146, 16, v137
	v_and_b32_e32 v147, 0xffff0000, v137
	v_lshlrev_b32_e32 v136, 16, v138
	v_and_b32_e32 v137, 0xffff0000, v138
	v_lshlrev_b32_e32 v138, 16, v139
	v_and_b32_e32 v139, 0xffff0000, v139
	s_waitcnt vmcnt(0)
	v_lshlrev_b32_e32 v148, 16, v140
	v_and_b32_e32 v149, 0xffff0000, v140
	v_lshlrev_b32_e32 v150, 16, v141
	v_and_b32_e32 v151, 0xffff0000, v141
	v_lshlrev_b32_e32 v140, 16, v142
	v_and_b32_e32 v141, 0xffff0000, v142
	v_lshlrev_b32_e32 v142, 16, v143
	v_and_b32_e32 v143, 0xffff0000, v143
	global_store_dwordx4 v[34:35], v[144:147], off
	global_store_dwordx4 v[34:35], v[136:139], off offset:16
	global_store_dwordx4 v[34:35], v[148:151], off offset:32
	global_store_dwordx4 v[34:35], v[140:143], off offset:48
.LBB0_410:
	s_or_b64 exec, exec, s[22:23]
	v_mov_b32_e32 v105, v104
	v_lshlrev_b32_e32 v3, 16, v29
	v_and_b32_e32 v7, 0xffff0000, v29
	v_pk_mul_f32 v[46:47], v[104:105], v[46:47]
	v_mov_b32_e32 v107, v106
	v_fma_f32 v39, v46, v3, 0
	v_fma_f32 v29, v47, v7, 0
	v_mov_b32_e32 v109, v108
	v_pk_mul_f32 v[40:41], v[104:105], v[40:41]
	v_pk_mul_f32 v[42:43], v[104:105], v[42:43]
	v_pk_mul_f32 v[50:51], v[106:107], v[50:51]
	v_lshlrev_b32_e32 v3, 16, v25
	v_and_b32_e32 v7, 0xffff0000, v25
	v_lshlrev_b32_e32 v35, 16, v31
	v_lshlrev_b32_e32 v34, 16, v30
	v_and_b32_e32 v31, 0xffff0000, v31
	v_and_b32_e32 v30, 0xffff0000, v30
	v_mov_b32_e32 v111, v110
	v_mov_b32_e32 v46, v40
	v_mov_b32_e32 v47, v42
	v_mov_b32_e32 v42, v41
	v_fmac_f32_e32 v39, v50, v3
	v_fmac_f32_e32 v29, v51, v7
	v_pk_mul_f32 v[24:25], v[106:107], v[66:67]
	v_pk_mul_f32 v[50:51], v[106:107], v[68:69]
	v_pk_mul_f32 v[68:69], v[106:107], v[74:75]
	v_pk_mul_f32 v[74:75], v[108:109], v[80:81]
	v_lshlrev_b32_e32 v3, 16, v17
	v_and_b32_e32 v7, 0xffff0000, v17
	v_lshlrev_b32_e32 v67, 16, v27
	v_lshlrev_b32_e32 v66, 16, v26
	v_and_b32_e32 v27, 0xffff0000, v27
	v_and_b32_e32 v26, 0xffff0000, v26
	v_fmac_f32_e32 v39, v74, v3
	v_fmac_f32_e32 v29, v75, v7
	v_pk_mul_f32 v[16:17], v[108:109], v[54:55]
	v_pk_mul_f32 v[56:57], v[108:109], v[56:57]
	v_pk_mul_f32 v[80:81], v[110:111], v[92:93]
	v_lshlrev_b32_e32 v3, 16, v21
	v_and_b32_e32 v7, 0xffff0000, v21
	v_pk_fma_f32 v[34:35], v[46:47], v[34:35], 0 op_sel_hi:[1,1,0]
	v_pk_fma_f32 v[30:31], v[42:43], v[30:31], 0 op_sel_hi:[1,1,0]
	v_mov_b32_e32 v42, v24
	v_mov_b32_e32 v43, v50
	v_mov_b32_e32 v50, v25
	v_pk_mul_f32 v[40:41], v[104:105], v[70:71]
	v_pk_mul_f32 v[48:49], v[104:105], v[72:73]
	v_lshlrev_b32_e32 v54, 16, v18
	v_and_b32_e32 v18, 0xffff0000, v18
	v_lshlrev_b32_e32 v55, 16, v19
	v_and_b32_e32 v19, 0xffff0000, v19
	v_fmac_f32_e32 v39, v80, v3
	v_fmac_f32_e32 v29, v81, v7
	v_pk_mul_f32 v[20:21], v[110:111], v[82:83]
	v_pk_mul_f32 v[80:81], v[110:111], v[84:85]
	v_pk_fma_f32 v[34:35], v[42:43], v[66:67], v[34:35]
	v_pk_fma_f32 v[24:25], v[50:51], v[26:27], v[30:31]
	v_mov_b32_e32 v26, v16
	v_mov_b32_e32 v27, v56
	v_mov_b32_e32 v56, v17
	v_mov_b32_e32 v64, v40
	v_mov_b32_e32 v65, v48
	v_mov_b32_e32 v48, v41
	v_lshlrev_b32_e32 v41, 16, v1
	v_lshlrev_b32_e32 v40, 16, v0
	v_pk_mul_f32 v[36:37], v[104:105], v[36:37]
	v_and_b32_e32 v1, 0xffff0000, v1
	v_and_b32_e32 v0, 0xffff0000, v0
	v_pk_mul_f32 v[70:71], v[106:107], v[76:77]
	v_pk_fma_f32 v[26:27], v[26:27], v[54:55], v[34:35]
	v_pk_fma_f32 v[16:17], v[56:57], v[18:19], v[24:25]
	v_lshlrev_b32_e32 v19, 16, v23
	v_lshlrev_b32_e32 v18, 16, v22
	v_mov_b32_e32 v24, v20
	v_mov_b32_e32 v25, v80
	v_and_b32_e32 v3, 0xffff0000, v2
	v_lshlrev_b32_e32 v2, 16, v2
	v_lshlrev_b32_e32 v73, 16, v5
	v_lshlrev_b32_e32 v72, 16, v4
	v_and_b32_e32 v5, 0xffff0000, v5
	v_and_b32_e32 v4, 0xffff0000, v4
	v_pk_mul_f32 v[52:53], v[106:107], v[52:53]
	v_pk_mul_f32 v[74:75], v[108:109], v[86:87]
	v_pk_mul_f32 v[78:79], v[108:109], v[88:89]
	v_and_b32_e32 v23, 0xffff0000, v23
	v_and_b32_e32 v22, 0xffff0000, v22
	v_mov_b32_e32 v80, v21
	v_pk_fma_f32 v[18:19], v[24:25], v[18:19], v[26:27]
	v_pk_fma_f32 v[24:25], v[64:65], v[40:41], 0 op_sel_hi:[1,1,0]
	v_pk_fma_f32 v[0:1], v[48:49], v[0:1], 0 op_sel_hi:[1,1,0]
	v_mov_b32_e32 v26, v68
	v_mov_b32_e32 v27, v70
	v_mov_b32_e32 v70, v69
	v_pk_fma_f32 v[2:3], v[36:37], v[2:3], 0 op_sel_hi:[1,1,0]
	v_and_b32_e32 v7, 0xffff0000, v6
	v_lshlrev_b32_e32 v6, 16, v6
	v_lshlrev_b32_e32 v76, 16, v8
	v_and_b32_e32 v8, 0xffff0000, v8
	v_lshlrev_b32_e32 v77, 16, v9
	v_and_b32_e32 v9, 0xffff0000, v9
	v_pk_mul_f32 v[62:63], v[108:109], v[62:63]
	v_pk_fma_f32 v[16:17], v[80:81], v[22:23], v[16:17]
	s_waitcnt lgkmcnt(0)
	v_pk_mul_f32 v[20:21], v[110:111], v[58:59]
	v_pk_mul_f32 v[22:23], v[110:111], v[60:61]
	v_pk_fma_f32 v[24:25], v[26:27], v[72:73], v[24:25]
	v_pk_fma_f32 v[0:1], v[70:71], v[4:5], v[0:1]
	v_mov_b32_e32 v4, v74
	v_mov_b32_e32 v5, v78
	v_mov_b32_e32 v78, v75
	v_pk_fma_f32 v[2:3], v[52:53], v[6:7], v[2:3]
	v_and_b32_e32 v7, 0xffff0000, v10
	v_lshlrev_b32_e32 v6, 16, v10
	v_pk_fma_f32 v[4:5], v[4:5], v[76:77], v[24:25]
	v_pk_fma_f32 v[0:1], v[78:79], v[8:9], v[0:1]
	v_lshlrev_b32_e32 v9, 16, v13
	v_lshlrev_b32_e32 v8, 16, v12
	v_mov_b32_e32 v24, v20
	v_mov_b32_e32 v25, v22
	v_pk_fma_f32 v[2:3], v[62:63], v[6:7], v[2:3]
	v_mul_f32_e32 v6, 0xbfb8aa3b, v44
	v_pk_fma_f32 v[4:5], v[24:25], v[8:9], v[4:5]
	v_pk_mul_f32 v[8:9], v[110:111], v[32:33]
	v_exp_f32_e32 v10, v6
	v_and_b32_e32 v7, 0xffff0000, v14
	v_lshlrev_b32_e32 v6, 16, v14
	v_pk_fma_f32 v[2:3], v[8:9], v[6:7], v[2:3]
	v_mul_f32_e32 v7, 0xbfb8aa3b, v38
	v_exp_f32_e32 v7, v7
	v_mul_f32_e32 v8, 0xbfb8aa3b, v28
	v_exp_f32_e32 v9, v8
	v_add_f32_e32 v6, 1.0, v10
	v_add_f32_e32 v7, 1.0, v7
	v_rcp_f32_e32 v8, v7
	v_add_f32_e32 v7, 1.0, v9
	v_mul_f32_e32 v9, 0xbfb8aa3b, v39
	v_exp_f32_e32 v9, v9
	v_mul_f32_e32 v10, 0xbfb8aa3b, v29
	v_exp_f32_e32 v11, v10
	v_rcp_f32_e32 v10, v7
	v_add_f32_e32 v7, 1.0, v9
	v_and_b32_e32 v13, 0xffff0000, v13
	v_and_b32_e32 v12, 0xffff0000, v12
	v_mov_b32_e32 v22, v21
	v_rcp_f32_e32 v9, v7
	v_add_f32_e32 v7, 1.0, v11
	v_mul_f32_e32 v11, 0xbfb8aa3b, v18
	v_pk_fma_f32 v[0:1], v[22:23], v[12:13], v[0:1]
	v_exp_f32_e32 v12, v11
	v_mul_f32_e32 v11, 0xbfb8aa3b, v16
	v_exp_f32_e32 v13, v11
	v_rcp_f32_e32 v11, v7
	v_add_f32_e32 v7, 1.0, v12
	v_rcp_f32_e32 v12, v7
	v_add_f32_e32 v7, 1.0, v13
	v_mul_f32_e32 v13, 0xbfb8aa3b, v19
	v_exp_f32_e32 v13, v13
	v_mul_f32_e32 v14, 0xbfb8aa3b, v17
	v_exp_f32_e32 v15, v14
	v_rcp_f32_e32 v14, v7
	v_add_f32_e32 v7, 1.0, v13
	v_rcp_f32_e32 v13, v7
	v_add_f32_e32 v7, 1.0, v15
	v_mul_f32_e32 v15, 0xbfb8aa3b, v4
	v_exp_f32_e32 v20, v15
	v_mul_f32_e32 v15, 0xbfb8aa3b, v0
	v_exp_f32_e32 v21, v15
	v_rcp_f32_e32 v15, v7
	v_add_f32_e32 v7, 1.0, v20
	v_rcp_f32_e32 v20, v7
	v_add_f32_e32 v7, 1.0, v21
	v_rcp_f32_e32 v22, v7
	v_mul_f32_e32 v7, 0xbfb8aa3b, v5
	v_mul_f32_e32 v21, 0xbfb8aa3b, v1
	v_exp_f32_e32 v7, v7
	v_exp_f32_e32 v23, v21
	v_mul_f32_e32 v21, 0xbfb8aa3b, v2
	v_exp_f32_e32 v24, v21
	v_and_b32_e32 v131, 64, v124
	v_xor_b32_e32 v30, 1, v124
	v_add_u32_e32 v32, 64, v131
	v_cmp_lt_i32_e32 vcc, v30, v32
	v_add_f32_e32 v7, 1.0, v7
	v_pk_mul_f32 v[8:9], v[38:39], v[8:9]
	v_cndmask_b32_e32 v30, v124, v30, vcc
	v_pk_mul_f32 v[10:11], v[28:29], v[10:11]
	v_rcp_f32_e32 v21, v7
	v_add_f32_e32 v23, 1.0, v23
	v_add_f32_e32 v7, 1.0, v24
	v_mul_f32_e32 v24, 0xbfb8aa3b, v3
	v_lshlrev_b32_e32 v135, 2, v30
	v_pk_mul_f32 v[28:29], v[8:9], v[8:9]
	v_pk_mul_f32 v[30:31], v[10:11], v[10:11]
	v_exp_f32_e32 v25, v24
	v_rcp_f32_e32 v23, v23
	v_add_f32_e32 v28, v28, v30
	v_mul_f32_e32 v24, 0xbfb8aa3b, v45
	v_pk_mul_f32 v[12:13], v[18:19], v[12:13]
	v_add_f32_e32 v28, v29, v28
	v_exp_f32_e32 v26, v24
	v_pk_mul_f32 v[14:15], v[16:17], v[14:15]
	v_pk_mul_f32 v[16:17], v[12:13], v[12:13]
	v_add_f32_e32 v28, v31, v28
	v_pk_mul_f32 v[18:19], v[14:15], v[14:15]
	v_add_f32_e32 v16, v16, v28
	v_rcp_f32_e32 v24, v7
	v_add_f32_e32 v7, 1.0, v25
	v_pk_mul_f32 v[4:5], v[4:5], v[20:21]
	v_pk_mul_f32 v[0:1], v[0:1], v[22:23]
	v_add_f32_e32 v16, v18, v16
	v_rcp_f32_e32 v25, v7
	v_mov_b32_e32 v20, v0
	v_mov_b32_e32 v21, v4
	v_add_f32_e32 v16, v17, v16
	v_add_f32_e32 v7, 1.0, v26
	v_pk_mul_f32 v[20:21], v[20:21], v[20:21]
	v_add_f32_e32 v16, v19, v16
	v_rcp_f32_e32 v6, v6
	v_rcp_f32_e32 v7, v7
	v_mov_b32_e32 v22, v1
	v_mov_b32_e32 v23, v5
	v_add_f32_e32 v16, v21, v16
	v_pk_mul_f32 v[22:23], v[22:23], v[22:23]
	v_add_f32_e32 v16, v20, v16
	v_pk_mul_f32 v[2:3], v[2:3], v[24:25]
	v_add_f32_e32 v16, v23, v16
	v_pk_mul_f32 v[24:25], v[2:3], v[2:3]
	v_add_f32_e32 v16, v22, v16
	v_pk_mul_f32 v[6:7], v[44:45], v[6:7]
	v_add_f32_e32 v16, v24, v16
	v_pk_mul_f32 v[26:27], v[6:7], v[6:7]
	v_add_f32_e32 v16, v25, v16
	v_add_f32_e32 v16, v27, v16
	v_add_f32_e32 v16, v26, v16
	ds_bpermute_b32 v17, v135, v16
	v_xor_b32_e32 v18, 2, v124
	v_cmp_lt_i32_e32 vcc, v18, v32
	v_lshl_or_b32 v96, v133, 1, v126
	v_lshl_add_u64 v[122:123], v[116:117], 0, v[96:97]
	v_cndmask_b32_e32 v18, v124, v18, vcc
	v_lshlrev_b32_e32 v137, 2, v18
	s_waitcnt lgkmcnt(0)
	v_add_f32_e32 v16, v16, v17
	ds_bpermute_b32 v17, v137, v16
	v_xor_b32_e32 v18, 4, v124
	v_cmp_lt_i32_e32 vcc, v18, v32
	s_waitcnt lgkmcnt(0)
	v_add_f32_e32 v16, v16, v17
	v_cndmask_b32_e32 v18, v124, v18, vcc
	v_lshlrev_b32_e32 v138, 2, v18
	ds_bpermute_b32 v17, v138, v16
	s_waitcnt lgkmcnt(0)
	v_add_f32_e32 v16, v16, v17
	v_add_f32_e32 v16, 0x358637bd, v16
	v_mul_f32_e32 v17, 0x4b800000, v16
	v_cmp_gt_f32_e32 vcc, s55, v16
	s_nop 1
	v_cndmask_b32_e32 v16, v16, v17, vcc
	v_rsq_f32_e32 v16, v16
	v_mul_lo_u32 v17, v99, s54
	v_mul_f32_e32 v18, 0x45800000, v16
	v_cndmask_b32_e32 v16, v16, v18, vcc
	v_mul_f32_e32 v16, 0x3db504f3, v16
	v_pk_mul_f32 v[18:19], v[0:1], v[16:17] op_sel_hi:[1,0]
	v_mov_b32_e32 v0, v2
	v_mov_b32_e32 v1, v7
	v_pk_mul_f32 v[20:21], v[0:1], v[16:17] op_sel_hi:[1,0]
	v_pk_mov_b32 v[0:1], v[2:3], v[6:7] op_sel:[1,0]
	v_pk_mul_f32 v[10:11], v[10:11], v[16:17] op_sel_hi:[1,0]
	v_pk_mul_f32 v[14:15], v[14:15], v[16:17] op_sel_hi:[1,0]
	v_pk_mul_f32 v[6:7], v[0:1], v[16:17] op_sel_hi:[1,0]
	v_lshlrev_b32_e32 v0, 1, v134
	v_pk_mul_f32 v[8:9], v[8:9], v[16:17] op_sel_hi:[1,0]
	v_pk_mul_f32 v[12:13], v[12:13], v[16:17] op_sel_hi:[1,0]
	v_add3_u32 v136, 0, v17, v0
	v_bfe_u32 v0, v15, 16, 1
	v_bfe_u32 v1, v14, 16, 1
	v_bfe_u32 v2, v11, 16, 1
	v_bfe_u32 v3, v10, 16, 1
	v_add3_u32 v10, v10, v3, s56
	v_add3_u32 v11, v11, v2, s56
	v_add3_u32 v1, v14, v1, s56
	v_add3_u32 v0, v15, v0, s56
	v_bfe_u32 v2, v8, 16, 1
	v_bfe_u32 v3, v9, 16, 1
	v_bfe_u32 v14, v12, 16, 1
	v_bfe_u32 v15, v13, 16, 1
	v_add3_u32 v13, v13, v15, s56
	v_add3_u32 v12, v12, v14, s56
	v_add3_u32 v3, v9, v3, s56
	v_add3_u32 v2, v8, v2, s56
	v_lshrrev_b32_e32 v8, 16, v2
	v_lshrrev_b32_e32 v9, 16, v3
	v_lshrrev_b32_e32 v2, 16, v12
	v_lshrrev_b32_e32 v3, 16, v13
	v_and_or_b32 v3, v0, s53, v3
	v_and_or_b32 v2, v1, s53, v2
	v_and_or_b32 v1, v11, s53, v9
	v_and_or_b32 v0, v10, s53, v8
	v_pk_mul_f32 v[4:5], v[4:5], v[16:17] op_sel_hi:[1,0]
	ds_write_b128 v136, v[0:3]
	v_bfe_u32 v0, v7, 16, 1
	v_bfe_u32 v1, v6, 16, 1
	v_bfe_u32 v2, v19, 16, 1
	v_bfe_u32 v3, v18, 16, 1
	v_add3_u32 v8, v18, v3, s56
	v_add3_u32 v9, v19, v2, s56
	v_add3_u32 v1, v6, v1, s56
	v_add3_u32 v0, v7, v0, s56
	v_bfe_u32 v2, v4, 16, 1
	v_bfe_u32 v3, v5, 16, 1
	v_bfe_u32 v6, v20, 16, 1
	v_bfe_u32 v7, v21, 16, 1
	v_add3_u32 v7, v21, v7, s56
	v_add3_u32 v6, v20, v6, s56
	v_add3_u32 v3, v5, v3, s56
	v_add3_u32 v2, v4, v2, s56
	v_lshrrev_b32_e32 v4, 16, v2
	v_lshrrev_b32_e32 v5, 16, v3
	v_lshrrev_b32_e32 v2, 16, v6
	v_lshrrev_b32_e32 v3, 16, v7
	v_and_or_b32 v3, v0, s53, v3
	v_and_or_b32 v2, v1, s53, v2
	v_and_or_b32 v1, v9, s53, v5
	v_and_or_b32 v0, v8, s53, v4
	ds_write_b128 v136, v[0:3] offset:16
	v_lshl_add_u64 v[0:1], v[94:95], 0, v[96:97]
	s_waitcnt vmcnt(0)
	s_nop 1
	v_mov_b32_e32 v72, v160
	v_mov_b32_e32 v73, v161
	v_mov_b32_e32 v74, v162
	v_mov_b32_e32 v75, v163
	v_mov_b32_e32 v12, v164
	v_mov_b32_e32 v13, v165
	v_mov_b32_e32 v14, v166
	v_mov_b32_e32 v15, v167
	v_lshl_add_u64 v[0:1], v[112:113], 0, v[96:97]
	v_mov_b32_e32 v28, v168
	v_mov_b32_e32 v29, v169
	v_mov_b32_e32 v30, v170
	v_mov_b32_e32 v31, v171
	v_mov_b32_e32 v8, v172
	v_mov_b32_e32 v9, v173
	v_mov_b32_e32 v10, v174
	v_mov_b32_e32 v11, v175
	v_lshl_add_u64 v[0:1], v[114:115], 0, v[96:97]
	v_mov_b32_e32 v24, v176
	v_mov_b32_e32 v25, v177
	v_mov_b32_e32 v26, v178
	v_mov_b32_e32 v27, v179
	v_mov_b32_e32 v4, v180
	v_mov_b32_e32 v5, v181
	v_mov_b32_e32 v6, v182
	v_mov_b32_e32 v7, v183
	v_mov_b32_e32 v16, v184
	v_mov_b32_e32 v17, v185
	v_mov_b32_e32 v18, v186
	v_mov_b32_e32 v19, v187
	s_nop 0
	v_mov_b32_e32 v0, v188
	v_mov_b32_e32 v1, v189
	v_mov_b32_e32 v2, v190
	v_mov_b32_e32 v3, v191
	ds_read_b128 v[88:91], v132 offset:2048
	ds_read_b128 v[84:87], v132 offset:2064
	ds_read_b128 v[76:79], v132 offset:2080
	ds_read_b128 v[54:57], v132 offset:2096
	s_waitcnt lgkmcnt(3)
	v_pk_mul_f32 v[20:21], v[104:105], v[88:89]
	s_waitcnt vmcnt(7)
	v_lshlrev_b32_e32 v22, 16, v72
	v_and_b32_e32 v23, 0xffff0000, v72
	v_fma_f32 v88, v20, v22, 0
	v_fma_f32 v72, v21, v23, 0
	s_waitcnt lgkmcnt(0)
	v_pk_mul_f32 v[20:21], v[104:105], v[56:57]
	s_waitcnt vmcnt(6)
	v_lshlrev_b32_e32 v22, 16, v15
	v_and_b32_e32 v15, 0xffff0000, v15
	v_fma_f32 v93, v20, v22, 0
	v_fma_f32 v92, v21, v15, 0
	ds_read_b128 v[80:83], v132 offset:2560
	ds_read_b128 v[64:67], v132 offset:2576
	ds_read_b128 v[46:49], v132 offset:2592
	ds_read_b128 v[40:43], v132 offset:2608
	s_waitcnt vmcnt(5)
	v_lshlrev_b32_e32 v15, 16, v28
	s_waitcnt lgkmcnt(3)
	v_pk_mul_f32 v[20:21], v[106:107], v[80:81]
	v_and_b32_e32 v22, 0xffff0000, v28
	v_fmac_f32_e32 v88, v20, v15
	v_fmac_f32_e32 v72, v21, v22
	s_waitcnt lgkmcnt(0)
	v_pk_mul_f32 v[20:21], v[106:107], v[42:43]
	s_waitcnt vmcnt(4)
	v_lshlrev_b32_e32 v15, 16, v11
	v_and_b32_e32 v11, 0xffff0000, v11
	v_fmac_f32_e32 v93, v20, v15
	v_fmac_f32_e32 v92, v21, v11
	ds_read_b128 v[68:71], v132 offset:3072
	ds_read_b128 v[50:53], v132 offset:3088
	ds_read_b128 v[42:45], v132 offset:3104
	ds_read_b128 v[36:39], v132 offset:3120
	s_waitcnt vmcnt(3)
	v_lshlrev_b32_e32 v11, 16, v24
	s_waitcnt lgkmcnt(3)
	v_pk_mul_f32 v[20:21], v[108:109], v[68:69]
	v_and_b32_e32 v15, 0xffff0000, v24
	v_fmac_f32_e32 v88, v20, v11
	v_fmac_f32_e32 v72, v21, v15
	s_waitcnt lgkmcnt(0)
	v_pk_mul_f32 v[20:21], v[108:109], v[38:39]
	s_waitcnt vmcnt(2)
	v_lshlrev_b32_e32 v11, 16, v7
	v_and_b32_e32 v7, 0xffff0000, v7
	v_fmac_f32_e32 v93, v20, v11
	v_fmac_f32_e32 v92, v21, v7
	ds_read_b128 v[60:63], v132 offset:3584
	ds_read_b128 v[56:59], v132 offset:3600
	s_waitcnt vmcnt(1)
	v_lshlrev_b32_e32 v7, 16, v16
	ds_read_b128 v[32:35], v132 offset:3616
	s_waitcnt lgkmcnt(2)
	v_pk_mul_f32 v[20:21], v[110:111], v[60:61]
	s_nop 0
	v_fmac_f32_e32 v88, v20, v7
	v_and_b32_e32 v7, 0xffff0000, v16
	v_fmac_f32_e32 v72, v21, v7
	ds_read_b128 v[20:23], v132 offset:3632
	s_waitcnt vmcnt(0)
	v_lshlrev_b32_e32 v7, 16, v3
	v_and_b32_e32 v3, 0xffff0000, v3
	s_waitcnt lgkmcnt(0)
	v_pk_mul_f32 v[22:23], v[110:111], v[22:23]
	s_nop 0
	v_fmac_f32_e32 v93, v22, v7
	v_fmac_f32_e32 v92, v23, v3
	s_and_saveexec_b64 s[22:23], s[4:5]
	s_cbranch_execz .LBB0_412
	global_load_dwordx4 v[140:143], v[122:123], off
	global_load_dwordx4 v[144:147], v[122:123], off offset:16
	v_mov_b32_e32 v121, v97
	v_lshl_add_u64 v[22:23], v[118:119], 0, v[120:121]
	s_waitcnt vmcnt(1)
	v_lshlrev_b32_e32 v120, 16, v140
	v_and_b32_e32 v121, 0xffff0000, v140
	v_lshlrev_b32_e32 v122, 16, v141
	v_and_b32_e32 v123, 0xffff0000, v141
	v_lshlrev_b32_e32 v140, 16, v142
	v_and_b32_e32 v141, 0xffff0000, v142
	v_lshlrev_b32_e32 v142, 16, v143
	v_and_b32_e32 v143, 0xffff0000, v143
	s_waitcnt vmcnt(0)
	v_lshlrev_b32_e32 v148, 16, v144
	v_and_b32_e32 v149, 0xffff0000, v144
	v_lshlrev_b32_e32 v150, 16, v145
	v_and_b32_e32 v151, 0xffff0000, v145
	v_lshlrev_b32_e32 v144, 16, v146
	v_and_b32_e32 v145, 0xffff0000, v146
	v_lshlrev_b32_e32 v146, 16, v147
	v_and_b32_e32 v147, 0xffff0000, v147
	global_store_dwordx4 v[22:23], v[120:123], off offset:2048
	global_store_dwordx4 v[22:23], v[140:143], off offset:2064
	global_store_dwordx4 v[22:23], v[148:151], off offset:2080
	global_store_dwordx4 v[22:23], v[144:147], off offset:2096
.LBB0_412:
	s_or_b64 exec, exec, s[22:23]
	v_pk_mul_f32 v[22:23], v[104:105], v[90:91]
	v_lshlrev_b32_e32 v3, 16, v73
	v_and_b32_e32 v7, 0xffff0000, v73
	v_fma_f32 v89, v22, v3, 0
	v_fma_f32 v73, v23, v7, 0
	v_pk_mul_f32 v[22:23], v[104:105], v[84:85]
	v_pk_mul_f32 v[38:39], v[104:105], v[86:87]
	v_mov_b32_e32 v68, v22
	v_mov_b32_e32 v69, v38
	v_mov_b32_e32 v38, v23
	v_pk_mul_f32 v[22:23], v[104:105], v[76:77]
	v_pk_mul_f32 v[76:77], v[104:105], v[78:79]
	v_mov_b32_e32 v80, v22
	v_mov_b32_e32 v81, v76
	v_mov_b32_e32 v76, v23
	v_pk_mul_f32 v[22:23], v[104:105], v[54:55]
	v_pk_mul_f32 v[54:55], v[106:107], v[82:83]
	v_lshlrev_b32_e32 v3, 16, v29
	v_and_b32_e32 v7, 0xffff0000, v29
	v_lshlrev_b32_e32 v61, 16, v75
	v_lshlrev_b32_e32 v60, 16, v74
	v_and_b32_e32 v75, 0xffff0000, v75
	v_and_b32_e32 v74, 0xffff0000, v74
	v_fmac_f32_e32 v89, v54, v3
	v_fmac_f32_e32 v73, v55, v7
	v_pk_mul_f32 v[28:29], v[106:107], v[64:65]
	v_pk_mul_f32 v[54:55], v[106:107], v[66:67]
	v_pk_mul_f32 v[70:71], v[108:109], v[70:71]
	v_lshlrev_b32_e32 v3, 16, v25
	v_and_b32_e32 v7, 0xffff0000, v25
	v_lshlrev_b32_e32 v65, 16, v31
	v_lshlrev_b32_e32 v64, 16, v30
	v_and_b32_e32 v31, 0xffff0000, v31
	v_and_b32_e32 v30, 0xffff0000, v30
	v_fmac_f32_e32 v89, v70, v3
	v_fmac_f32_e32 v73, v71, v7
	v_pk_mul_f32 v[24:25], v[108:109], v[50:51]
	v_pk_mul_f32 v[52:53], v[108:109], v[52:53]
	v_lshlrev_b32_e32 v3, 16, v17
	v_and_b32_e32 v7, 0xffff0000, v17
	v_pk_mul_f32 v[16:17], v[110:111], v[56:57]
	v_pk_mul_f32 v[56:57], v[110:111], v[58:59]
	v_pk_fma_f32 v[58:59], v[68:69], v[60:61], 0 op_sel_hi:[1,1,0]
	v_pk_fma_f32 v[38:39], v[38:39], v[74:75], 0 op_sel_hi:[1,1,0]
	v_mov_b32_e32 v60, v28
	v_mov_b32_e32 v61, v54
	v_mov_b32_e32 v54, v29
	v_lshlrev_b32_e32 v50, 16, v26
	v_and_b32_e32 v26, 0xffff0000, v26
	v_lshlrev_b32_e32 v51, 16, v27
	v_and_b32_e32 v27, 0xffff0000, v27
	v_pk_fma_f32 v[58:59], v[60:61], v[64:65], v[58:59]
	v_pk_fma_f32 v[28:29], v[54:55], v[30:31], v[38:39]
	v_mov_b32_e32 v30, v24
	v_mov_b32_e32 v31, v52
	v_mov_b32_e32 v52, v25
	v_lshlrev_b32_e32 v79, 16, v13
	v_lshlrev_b32_e32 v78, 16, v12
	v_and_b32_e32 v13, 0xffff0000, v13
	v_and_b32_e32 v12, 0xffff0000, v12
	v_pk_mul_f32 v[46:47], v[106:107], v[46:47]
	v_pk_mul_f32 v[48:49], v[106:107], v[48:49]
	v_pk_fma_f32 v[30:31], v[30:31], v[50:51], v[58:59]
	v_pk_fma_f32 v[24:25], v[52:53], v[26:27], v[28:29]
	v_lshlrev_b32_e32 v27, 16, v19
	v_lshlrev_b32_e32 v26, 16, v18
	v_mov_b32_e32 v28, v16
	v_mov_b32_e32 v29, v56
	v_lshlrev_b32_e32 v67, 16, v9
	v_lshlrev_b32_e32 v66, 16, v8
	v_and_b32_e32 v9, 0xffff0000, v9
	v_and_b32_e32 v8, 0xffff0000, v8
	v_pk_mul_f32 v[42:43], v[108:109], v[42:43]
	v_pk_mul_f32 v[44:45], v[108:109], v[44:45]
	v_and_b32_e32 v19, 0xffff0000, v19
	v_and_b32_e32 v18, 0xffff0000, v18
	v_mov_b32_e32 v56, v17
	v_pk_fma_f32 v[16:17], v[28:29], v[26:27], v[30:31]
	v_pk_fma_f32 v[28:29], v[80:81], v[78:79], 0 op_sel_hi:[1,1,0]
	v_pk_fma_f32 v[12:13], v[76:77], v[12:13], 0 op_sel_hi:[1,1,0]
	v_mov_b32_e32 v30, v46
	v_mov_b32_e32 v31, v48
	v_mov_b32_e32 v48, v47
	v_lshlrev_b32_e32 v70, 16, v4
	v_and_b32_e32 v4, 0xffff0000, v4
	v_lshlrev_b32_e32 v71, 16, v5
	v_and_b32_e32 v5, 0xffff0000, v5
	v_pk_fma_f32 v[18:19], v[56:57], v[18:19], v[24:25]
	v_pk_mul_f32 v[24:25], v[110:111], v[32:33]
	v_pk_mul_f32 v[26:27], v[110:111], v[34:35]
	v_pk_fma_f32 v[28:29], v[30:31], v[66:67], v[28:29]
	v_pk_fma_f32 v[8:9], v[48:49], v[8:9], v[12:13]
	v_mov_b32_e32 v12, v42
	v_mov_b32_e32 v13, v44
	v_mov_b32_e32 v44, v43
	v_pk_fma_f32 v[12:13], v[12:13], v[70:71], v[28:29]
	v_pk_fma_f32 v[4:5], v[44:45], v[4:5], v[8:9]
	v_lshlrev_b32_e32 v9, 16, v1
	v_lshlrev_b32_e32 v8, 16, v0
	v_mov_b32_e32 v28, v24
	v_mov_b32_e32 v29, v26
	v_pk_fma_f32 v[8:9], v[28:29], v[8:9], v[12:13]
	v_and_b32_e32 v13, 0xffff0000, v14
	v_lshlrev_b32_e32 v12, 16, v14
	v_pk_mul_f32 v[40:41], v[106:107], v[40:41]
	v_pk_mul_f32 v[62:63], v[110:111], v[62:63]
	v_pk_fma_f32 v[12:13], v[22:23], v[12:13], 0 op_sel_hi:[1,1,0]
	v_and_b32_e32 v11, 0xffff0000, v10
	v_lshlrev_b32_e32 v10, 16, v10
	v_pk_mul_f32 v[36:37], v[108:109], v[36:37]
	v_fmac_f32_e32 v89, v62, v3
	v_fmac_f32_e32 v73, v63, v7
	v_and_b32_e32 v1, 0xffff0000, v1
	v_and_b32_e32 v0, 0xffff0000, v0
	v_mov_b32_e32 v26, v25
	v_pk_fma_f32 v[10:11], v[40:41], v[10:11], v[12:13]
	v_and_b32_e32 v7, 0xffff0000, v6
	v_lshlrev_b32_e32 v6, 16, v6
	v_mul_f32_e32 v3, 0xbfb8aa3b, v92
	v_pk_fma_f32 v[0:1], v[26:27], v[0:1], v[4:5]
	v_pk_mul_f32 v[4:5], v[110:111], v[20:21]
	v_pk_fma_f32 v[6:7], v[36:37], v[6:7], v[10:11]
	v_exp_f32_e32 v10, v3
	v_and_b32_e32 v3, 0xffff0000, v2
	v_lshlrev_b32_e32 v2, 16, v2
	v_pk_fma_f32 v[2:3], v[4:5], v[2:3], v[6:7]
	v_mul_f32_e32 v5, 0xbfb8aa3b, v88
	v_exp_f32_e32 v5, v5
	v_mul_f32_e32 v6, 0xbfb8aa3b, v72
	v_exp_f32_e32 v7, v6
	v_add_f32_e32 v4, 1.0, v10
	v_add_f32_e32 v5, 1.0, v5
	v_rcp_f32_e32 v6, v5
	v_add_f32_e32 v5, 1.0, v7
	v_mul_f32_e32 v7, 0xbfb8aa3b, v89
	v_exp_f32_e32 v7, v7
	v_mul_f32_e32 v10, 0xbfb8aa3b, v73
	v_exp_f32_e32 v11, v10
	v_rcp_f32_e32 v10, v5
	v_add_f32_e32 v5, 1.0, v7
	v_rcp_f32_e32 v7, v5
	v_add_f32_e32 v5, 1.0, v11
	v_mul_f32_e32 v11, 0xbfb8aa3b, v16
	v_exp_f32_e32 v12, v11
	v_mul_f32_e32 v11, 0xbfb8aa3b, v18
	v_exp_f32_e32 v13, v11
	v_rcp_f32_e32 v11, v5
	v_add_f32_e32 v5, 1.0, v12
	v_rcp_f32_e32 v12, v5
	v_add_f32_e32 v5, 1.0, v13
	v_mul_f32_e32 v13, 0xbfb8aa3b, v17
	v_exp_f32_e32 v13, v13
	v_mul_f32_e32 v14, 0xbfb8aa3b, v19
	v_exp_f32_e32 v15, v14
	v_rcp_f32_e32 v14, v5
	v_add_f32_e32 v5, 1.0, v13
	v_rcp_f32_e32 v13, v5
	v_add_f32_e32 v5, 1.0, v15
	v_mul_f32_e32 v15, 0xbfb8aa3b, v8
	v_exp_f32_e32 v20, v15
	v_mul_f32_e32 v15, 0xbfb8aa3b, v0
	v_exp_f32_e32 v21, v15
	v_rcp_f32_e32 v15, v5
	v_add_f32_e32 v5, 1.0, v20
	v_rcp_f32_e32 v20, v5
	v_add_f32_e32 v5, 1.0, v21
	v_rcp_f32_e32 v22, v5
	v_mul_f32_e32 v5, 0xbfb8aa3b, v9
	v_mul_f32_e32 v21, 0xbfb8aa3b, v1
	v_exp_f32_e32 v5, v5
	v_exp_f32_e32 v23, v21
	v_mul_f32_e32 v21, 0xbfb8aa3b, v2
	v_exp_f32_e32 v24, v21
	v_add_f32_e32 v5, 1.0, v5
	v_pk_mul_f32 v[6:7], v[88:89], v[6:7]
	v_pk_mul_f32 v[10:11], v[72:73], v[10:11]
	v_rcp_f32_e32 v21, v5
	v_add_f32_e32 v23, 1.0, v23
	v_add_f32_e32 v5, 1.0, v24
	v_mul_f32_e32 v24, 0xbfb8aa3b, v3
	v_pk_mul_f32 v[28:29], v[6:7], v[6:7]
	v_pk_mul_f32 v[30:31], v[10:11], v[10:11]
	v_exp_f32_e32 v25, v24
	v_rcp_f32_e32 v23, v23
	v_add_f32_e32 v28, v28, v30
	v_mul_f32_e32 v24, 0xbfb8aa3b, v93
	v_pk_mul_f32 v[12:13], v[16:17], v[12:13]
	v_add_f32_e32 v28, v29, v28
	v_exp_f32_e32 v26, v24
	v_pk_mul_f32 v[14:15], v[18:19], v[14:15]
	v_pk_mul_f32 v[16:17], v[12:13], v[12:13]
	v_add_f32_e32 v28, v31, v28
	v_pk_mul_f32 v[18:19], v[14:15], v[14:15]
	v_add_f32_e32 v16, v16, v28
	v_rcp_f32_e32 v24, v5
	v_add_f32_e32 v5, 1.0, v25
	v_pk_mul_f32 v[8:9], v[8:9], v[20:21]
	v_pk_mul_f32 v[0:1], v[0:1], v[22:23]
	v_add_f32_e32 v16, v18, v16
	v_rcp_f32_e32 v25, v5
	v_mov_b32_e32 v20, v0
	v_mov_b32_e32 v21, v8
	v_add_f32_e32 v16, v17, v16
	v_add_f32_e32 v5, 1.0, v26
	v_pk_mul_f32 v[20:21], v[20:21], v[20:21]
	v_add_f32_e32 v16, v19, v16
	v_rcp_f32_e32 v4, v4
	v_rcp_f32_e32 v5, v5
	v_mov_b32_e32 v22, v1
	v_mov_b32_e32 v23, v9
	v_add_f32_e32 v16, v21, v16
	v_pk_mul_f32 v[22:23], v[22:23], v[22:23]
	v_add_f32_e32 v16, v20, v16
	v_pk_mul_f32 v[24:25], v[2:3], v[24:25]
	v_add_f32_e32 v16, v23, v16
	v_pk_mul_f32 v[2:3], v[24:25], v[24:25]
	v_add_f32_e32 v16, v22, v16
	v_pk_mul_f32 v[26:27], v[92:93], v[4:5]
	v_add_f32_e32 v2, v2, v16
	v_pk_mul_f32 v[4:5], v[26:27], v[26:27]
	v_add_f32_e32 v2, v3, v2
	v_add_f32_e32 v2, v5, v2
	v_add_f32_e32 v2, v4, v2
	ds_bpermute_b32 v3, v135, v2
	v_lshlrev_b32_e32 v120, 2, v134
	v_mul_lo_u32 v121, v99, s57
	v_or_b32_e32 v122, 0x400, v133
	v_lshlrev_b32_e32 v96, 1, v122
	s_waitcnt lgkmcnt(0)
	v_add_f32_e32 v2, v2, v3
	ds_bpermute_b32 v3, v137, v2
	s_waitcnt lgkmcnt(0)
	v_add_f32_e32 v2, v2, v3
	ds_bpermute_b32 v3, v138, v2
	s_waitcnt lgkmcnt(0)
	v_add_f32_e32 v2, v2, v3
	v_add_f32_e32 v2, 0x358637bd, v2
	v_mul_f32_e32 v3, 0x4b800000, v2
	v_cmp_gt_f32_e32 vcc, s55, v2
	s_nop 1
	v_cndmask_b32_e32 v2, v2, v3, vcc
	v_rsq_f32_e32 v2, v2
	s_nop 0
	v_mul_f32_e32 v3, 0x45800000, v2
	v_cndmask_b32_e32 v16, v2, v3, vcc
	v_pk_mul_f32 v[18:19], v[6:7], v[16:17] op_sel_hi:[1,0]
	v_pk_mul_f32 v[2:3], v[10:11], v[16:17] op_sel_hi:[1,0]
	v_pk_mul_f32 v[6:7], v[0:1], v[16:17] op_sel_hi:[1,0]
	v_mov_b32_e32 v0, v24
	v_mov_b32_e32 v1, v27
	v_pk_mul_f32 v[20:21], v[12:13], v[16:17] op_sel_hi:[1,0]
	v_pk_mul_f32 v[22:23], v[0:1], v[16:17] op_sel_hi:[1,0]
	v_pk_mov_b32 v[0:1], v[24:25], v[26:27] op_sel:[1,0]
	v_bfe_u32 v11, v2, 16, 1
	v_pk_mul_f32 v[4:5], v[14:15], v[16:17] op_sel_hi:[1,0]
	v_pk_mul_f32 v[14:15], v[8:9], v[16:17] op_sel_hi:[1,0]
	v_pk_mul_f32 v[8:9], v[0:1], v[16:17] op_sel_hi:[1,0]
	v_add3_u32 v16, v2, v11, s56
	v_bfe_u32 v11, v18, 16, 1
	v_bfe_u32 v12, v19, 16, 1
	v_bfe_u32 v13, v20, 16, 1
	v_bfe_u32 v17, v21, 16, 1
	v_bfe_u32 v0, v5, 16, 1
	v_bfe_u32 v1, v4, 16, 1
	v_bfe_u32 v10, v3, 16, 1
	v_add3_u32 v17, v21, v17, s56
	v_add3_u32 v13, v20, v13, s56
	v_add3_u32 v12, v19, v12, s56
	v_add3_u32 v11, v18, v11, s56
	v_add3_u32 v10, v3, v10, s56
	v_add3_u32 v1, v4, v1, s56
	v_add3_u32 v0, v5, v0, s56
	v_lshrrev_b32_e32 v24, 16, v11
	v_lshrrev_b32_e32 v11, 16, v12
	v_lshrrev_b32_e32 v12, 16, v13
	v_lshrrev_b32_e32 v13, 16, v17
	v_and_or_b32 v13, v0, s53, v13
	v_and_or_b32 v12, v1, s53, v12
	v_and_or_b32 v11, v10, s53, v11
	v_and_or_b32 v10, v16, s53, v24
	ds_write_b128 v136, v[10:13] offset:17408
	v_bfe_u32 v11, v6, 16, 1
	v_add3_u32 v16, v6, v11, s56
	v_bfe_u32 v11, v14, 16, 1
	v_bfe_u32 v12, v15, 16, 1
	v_bfe_u32 v13, v22, 16, 1
	v_bfe_u32 v17, v23, 16, 1
	v_bfe_u32 v0, v9, 16, 1
	v_bfe_u32 v1, v8, 16, 1
	v_bfe_u32 v10, v7, 16, 1
	v_add3_u32 v17, v23, v17, s56
	v_add3_u32 v13, v22, v13, s56
	v_add3_u32 v12, v15, v12, s56
	v_add3_u32 v11, v14, v11, s56
	v_add3_u32 v10, v7, v10, s56
	v_add3_u32 v1, v8, v1, s56
	v_add3_u32 v0, v9, v0, s56
	v_lshrrev_b32_e32 v24, 16, v11
	v_lshrrev_b32_e32 v11, 16, v12
	v_lshrrev_b32_e32 v12, 16, v13
	v_lshrrev_b32_e32 v13, 16, v17
	v_and_or_b32 v13, v0, s53, v13
	v_and_or_b32 v12, v1, s53, v12
	v_and_or_b32 v11, v10, s53, v11
	v_and_or_b32 v10, v16, s53, v24
	ds_write_b128 v136, v[10:13] offset:17424
	v_add3_u32 v10, 0, v120, v121
	v_mov_b32_e32 v0, v18
	v_mov_b32_e32 v1, v2
	v_mov_b32_e32 v2, v19
	ds_write_b128 v10, v[0:3] offset:34816
	v_mov_b32_e32 v2, v20
	v_mov_b32_e32 v3, v4
	v_mov_b32_e32 v4, v21
	ds_write_b128 v10, v[2:5] offset:34832
	v_mov_b32_e32 v4, v14
	v_mov_b32_e32 v5, v6
	v_mov_b32_e32 v6, v15
	ds_write_b128 v10, v[4:7] offset:34848
	v_mov_b32_e32 v6, v22
	v_mov_b32_e32 v7, v8
	v_mov_b32_e32 v8, v23
	ds_write_b128 v10, v[6:9] offset:34864
	v_lshl_add_u64 v[0:1], v[94:95], 0, v[96:97]
	s_waitcnt vmcnt(0)
	s_nop 1
	v_mov_b32_e32 v28, v192
	v_mov_b32_e32 v29, v193
	v_mov_b32_e32 v30, v194
	v_mov_b32_e32 v31, v195
	v_mov_b32_e32 v12, v196
	v_mov_b32_e32 v13, v197
	v_mov_b32_e32 v14, v198
	v_mov_b32_e32 v15, v199
	v_lshl_add_u64 v[0:1], v[112:113], 0, v[96:97]
	v_mov_b32_e32 v24, v200
	v_mov_b32_e32 v25, v201
	v_mov_b32_e32 v26, v202
	v_mov_b32_e32 v27, v203
	v_mov_b32_e32 v8, v204
	v_mov_b32_e32 v9, v205
	v_mov_b32_e32 v10, v206
	v_mov_b32_e32 v11, v207
	v_lshl_add_u64 v[0:1], v[114:115], 0, v[96:97]
	v_mov_b32_e32 v20, v208
	v_mov_b32_e32 v21, v209
	v_mov_b32_e32 v22, v210
	v_mov_b32_e32 v23, v211
	v_mov_b32_e32 v4, v212
	v_mov_b32_e32 v5, v213
	v_mov_b32_e32 v6, v214
	v_mov_b32_e32 v7, v215
	v_lshl_add_u64 v[112:113], v[116:117], 0, v[96:97]
	v_mov_b32_e32 v16, v216
	v_mov_b32_e32 v17, v217
	v_mov_b32_e32 v18, v218
	v_mov_b32_e32 v19, v219
	v_mov_b32_e32 v0, v220
	v_mov_b32_e32 v1, v221
	v_mov_b32_e32 v2, v222
	v_mov_b32_e32 v3, v223
	ds_read_b128 v[56:59], v132 offset:4096
	ds_read_b128 v[52:55], v132 offset:4112
	ds_read_b128 v[44:47], v132 offset:4128
	ds_read_b128 v[48:51], v132 offset:4144
	s_waitcnt lgkmcnt(3)
	v_pk_mul_f32 v[32:33], v[104:105], v[56:57]
	s_waitcnt vmcnt(7)
	v_lshlrev_b32_e32 v34, 16, v28
	v_and_b32_e32 v28, 0xffff0000, v28
	v_fma_f32 v56, v32, v34, 0
	v_fma_f32 v57, v33, v28, 0
	s_waitcnt lgkmcnt(0)
	v_pk_mul_f32 v[32:33], v[104:105], v[50:51]
	s_waitcnt vmcnt(6)
	v_lshlrev_b32_e32 v28, 16, v15
	v_and_b32_e32 v15, 0xffff0000, v15
	v_fma_f32 v50, v32, v28, 0
	v_fma_f32 v51, v33, v15, 0
	ds_read_b128 v[72:75], v132 offset:4608
	ds_read_b128 v[68:71], v132 offset:4624
	ds_read_b128 v[60:63], v132 offset:4640
	ds_read_b128 v[64:67], v132 offset:4656
	s_waitcnt vmcnt(5)
	v_lshlrev_b32_e32 v15, 16, v24
	s_waitcnt lgkmcnt(3)
	v_pk_mul_f32 v[32:33], v[106:107], v[72:73]
	v_and_b32_e32 v24, 0xffff0000, v24
	v_fmac_f32_e32 v56, v32, v15
	v_fmac_f32_e32 v57, v33, v24
	s_waitcnt lgkmcnt(0)
	v_pk_mul_f32 v[32:33], v[106:107], v[66:67]
	s_waitcnt vmcnt(4)
	v_lshlrev_b32_e32 v15, 16, v11
	v_and_b32_e32 v11, 0xffff0000, v11
	v_fmac_f32_e32 v50, v32, v15
	v_fmac_f32_e32 v51, v33, v11
	ds_read_b128 v[88:91], v132 offset:5120
	ds_read_b128 v[84:87], v132 offset:5136
	ds_read_b128 v[76:79], v132 offset:5152
	ds_read_b128 v[80:83], v132 offset:5168
	s_waitcnt vmcnt(3)
	v_lshlrev_b32_e32 v11, 16, v20
	s_waitcnt lgkmcnt(3)
	v_pk_mul_f32 v[32:33], v[108:109], v[88:89]
	v_and_b32_e32 v15, 0xffff0000, v20
	v_fmac_f32_e32 v56, v32, v11
	v_fmac_f32_e32 v57, v33, v15
	s_waitcnt lgkmcnt(0)
	v_pk_mul_f32 v[32:33], v[108:109], v[82:83]
	s_waitcnt vmcnt(2)
	v_lshlrev_b32_e32 v11, 16, v7
	v_and_b32_e32 v7, 0xffff0000, v7
	v_fmac_f32_e32 v50, v32, v11
	v_fmac_f32_e32 v51, v33, v7
	ds_read_b128 v[92:95], v132 offset:5632
	ds_read_b128 v[40:43], v132 offset:5648
	ds_read_b128 v[36:39], v132 offset:5664
	ds_read_b128 v[32:35], v132 offset:5680
	s_waitcnt vmcnt(1)
	v_lshlrev_b32_e32 v7, 16, v16
	s_waitcnt lgkmcnt(3)
	v_pk_mul_f32 v[66:67], v[110:111], v[92:93]
	v_and_b32_e32 v11, 0xffff0000, v16
	v_fmac_f32_e32 v56, v66, v7
	s_waitcnt lgkmcnt(0)
	v_pk_mul_f32 v[34:35], v[110:111], v[34:35]
	s_waitcnt vmcnt(0)
	v_lshlrev_b32_e32 v7, 16, v3
	v_and_b32_e32 v3, 0xffff0000, v3
	v_fmac_f32_e32 v57, v67, v11
	v_fmac_f32_e32 v50, v34, v7
	v_fmac_f32_e32 v51, v35, v3
	s_and_saveexec_b64 s[22:23], s[4:5]
	s_cbranch_execz .LBB0_414
	global_load_dwordx4 v[114:117], v[112:113], off
	global_load_dwordx4 v[132:135], v[112:113], off offset:16
	v_lshlrev_b32_e32 v96, 2, v122
	v_lshl_add_u64 v[34:35], v[118:119], 0, v[96:97]
	s_waitcnt vmcnt(1)
	v_lshlrev_b32_e32 v112, 16, v114
	v_and_b32_e32 v113, 0xffff0000, v114
	v_lshlrev_b32_e32 v114, 16, v115
	v_and_b32_e32 v115, 0xffff0000, v115
	v_lshlrev_b32_e32 v136, 16, v116
	v_and_b32_e32 v137, 0xffff0000, v116
	v_lshlrev_b32_e32 v138, 16, v117
	v_and_b32_e32 v139, 0xffff0000, v117
	s_waitcnt vmcnt(0)
	v_lshlrev_b32_e32 v116, 16, v132
	v_and_b32_e32 v117, 0xffff0000, v132
	v_lshlrev_b32_e32 v118, 16, v133
	v_and_b32_e32 v119, 0xffff0000, v133
	v_lshlrev_b32_e32 v132, 16, v134
	v_and_b32_e32 v133, 0xffff0000, v134
	v_lshlrev_b32_e32 v134, 16, v135
	v_and_b32_e32 v135, 0xffff0000, v135
	global_store_dwordx4 v[34:35], v[112:115], off
	global_store_dwordx4 v[34:35], v[136:139], off offset:16
	global_store_dwordx4 v[34:35], v[116:119], off offset:32
	global_store_dwordx4 v[34:35], v[132:135], off offset:48
